# saddr-form LDS-DMA addressing and loop-invariant LDS base in the Win0 and RetOut K-loops
# speedup vs baseline: 1.0021x; 1.0021x over previous
; #define PG8_STAGE(bufoff, gbase, voff) do { _Pragma("unroll") for (int _i = 0; _i < 2; ++_i) \
;         __builtin_amdgcn_global_load_lds((const unsigned*)((const char*)(gbase) + (voff)[_i]), (LAS unsigned*)(lds + (bufoff) + ldsw + _i * 8192), 16, 0, 0); } while (0)
; #define PG8_LDA(dst, b, h) do { _Pragma("unroll") for (int m = 0; m < 4; ++m) _Pragma("unroll") for (int k = 0; k < 2; ++k) dst[m][k] = *(const LAS bf16x8*)(lds + PG8_SA(b, h) + aoff + m * 2048 + k * 1024); } while (0)
; #define PG8_LDB(dst, b, h) do { _Pragma("unroll") for (int n = 0; n < 2; ++n) _Pragma("unroll") for (int k = 0; k < 2; ++k) dst[n][k] = *(const LAS bf16x8*)(lds + PG8_SB(b, h) + boff + n * 2048 + k * 1024); } while (0)
; #define PG8_MMA(ai, bj, At, Bt) do { __builtin_amdgcn_s_setprio(1); _Pragma("unroll") for (int m = 0; m < 4; ++m) _Pragma("unroll") for (int n = 0; n < 2; ++n) _Pragma("unroll") for (int k = 0; k < 2; ++k) \
;         acc[ai][bj][m][n] = __builtin_amdgcn_mfma_f32_16x16x32_bf16(Bt[n][k], At[m][k], acc[ai][bj][m][n], 0, 0, 0); __builtin_amdgcn_s_setprio(0); } while (0)
; #define PG8_WAIT_V(n) asm volatile("s_waitcnt vmcnt(" #n ")" ::: "memory")
; #define PG8_WAIT_L(n) asm volatile("s_waitcnt lgkmcnt(" #n ")" ::: "memory")
; #define PG8_BAR __builtin_amdgcn_s_barrier()
; #define PG8_SCHED __builtin_amdgcn_sched_barrier(0)
; template <class Epi>
; __device__ __forceinline__ void gemm_phase(LAS unsigned char* lds, const Gemm g, const Epi& E) {
;     ...
;         for (int t = 0; t < nt; t += 2) {
;             const bool last = (t == nt - 2);
;             const char* a1 = cA + (size_t)(t + 1) * kstep;
;             const char* a2 = last ? nA : cA + (size_t)(t + 2) * kstep; const char* b2 = last ? nB : cB + (size_t)(t + 2) * kstep;
;             const char* a3 = a2 + kstep; const char* b3 = b2 + kstep;
;             PG8_LDB(B0, 0, 0); PG8_LDB(B1, 0, 1); PG8_SCHED; PG8_LDA(At, 0, 0); PG8_STAGE(PG8_SA(1, 1), a1 + hstepA, voffA);
;             PG8_WAIT_V(8); PG8_WAIT_L(0); PG8_BAR; PG8_MMA(0, 0, At, B0); PG8_MMA(0, 1, At, B1); PG8_BAR; PG8_SCHED;
;     ...
; #pragma unroll
;         for (int a = 0; a < 2; ++a)
; #pragma unroll
;             for (int b = 0; b < 2; ++b)
; #pragma unroll
;                 for (int m = 0; m < 4; ++m)
; #pragma unroll
;                     for (int n = 0; n < 2; ++n) acc[a][b][m][n] = (f32x4){0.f, 0.f, 0.f, 0.f};
;         cur = nxt; cA = nA; cB = nB; ++ui;
.LBB0_287:
	s_ashr_i32 s47, s46, 31
	s_lshl_b64 s[24:25], s[46:47], 20
	v_readlane_b32 s38, v255, 14
	s_add_u32 s56, s38, s24
	v_readlane_b32 s24, v255, 12
	s_addc_u32 s57, s24, s25
	s_and_b64 s[24:25], s[42:43], exec
	s_cselect_b32 s47, s57, s21
	s_cselect_b32 s66, s56, s20
	s_ashr_i32 s49, s48, 31
	s_lshl_b64 s[24:25], s[48:49], 20
	s_add_u32 s38, s64, s24
	s_addc_u32 s39, s65, s25
	s_and_b64 s[24:25], s[42:43], exec
	s_cselect_b32 s49, s39, s83
	s_cselect_b32 s69, s38, s82
	s_add_u32 s20, s20, 0x80080
	s_addc_u32 s21, s21, 0
	s_add_u32 s82, s82, 0x100
	v_mov_b64_e32 v[0:1], 0
	v_mov_b64_e32 v[2:3], 0
	v_mov_b64_e32 v[4:5], 0
	v_mov_b64_e32 v[6:7], 0
	v_mov_b64_e32 v[8:9], 0
	v_mov_b64_e32 v[10:11], 0
	v_mov_b64_e32 v[12:13], 0
	v_mov_b64_e32 v[14:15], 0
	v_mov_b64_e32 v[16:17], 0
	v_mov_b64_e32 v[18:19], 0
	v_mov_b64_e32 v[20:21], 0
	v_mov_b64_e32 v[22:23], 0
	v_mov_b64_e32 v[24:25], 0
	v_mov_b64_e32 v[26:27], 0
	v_mov_b64_e32 v[28:29], 0
	v_mov_b64_e32 v[30:31], 0
	v_mov_b64_e32 v[32:33], 0
	v_mov_b64_e32 v[34:35], 0
	v_mov_b64_e32 v[36:37], 0
	v_mov_b64_e32 v[38:39], 0
	v_mov_b64_e32 v[40:41], 0
	v_mov_b64_e32 v[42:43], 0
	v_mov_b64_e32 v[44:45], 0
	v_mov_b64_e32 v[46:47], 0
	v_mov_b64_e32 v[48:49], 0
	v_mov_b64_e32 v[50:51], 0
	v_mov_b64_e32 v[52:53], 0
	v_mov_b64_e32 v[54:55], 0
	v_mov_b64_e32 v[56:57], 0
	v_mov_b64_e32 v[58:59], 0
	v_mov_b64_e32 v[60:61], 0
	v_mov_b64_e32 v[62:63], 0
	v_mov_b64_e32 v[64:65], 0
	v_mov_b64_e32 v[66:67], 0
	v_mov_b64_e32 v[68:69], 0
	v_mov_b64_e32 v[70:71], 0
	v_mov_b64_e32 v[72:73], 0
	v_mov_b64_e32 v[74:75], 0
	v_mov_b64_e32 v[76:77], 0
	v_mov_b64_e32 v[78:79], 0
	v_mov_b64_e32 v[80:81], 0
	v_mov_b64_e32 v[82:83], 0
	v_mov_b64_e32 v[84:85], 0
	v_mov_b64_e32 v[86:87], 0
	v_mov_b64_e32 v[88:89], 0
	v_mov_b64_e32 v[90:91], 0
	v_mov_b64_e32 v[92:93], 0
	v_mov_b64_e32 v[94:95], 0
	v_mov_b64_e32 v[96:97], 0
	v_mov_b64_e32 v[98:99], 0
	v_mov_b64_e32 v[100:101], 0
	v_mov_b64_e32 v[102:103], 0
	v_mov_b64_e32 v[104:105], 0
	v_mov_b64_e32 v[106:107], 0
	v_mov_b64_e32 v[108:109], 0
	v_mov_b64_e32 v[110:111], 0
	v_mov_b64_e32 v[112:113], 0
	v_mov_b64_e32 v[114:115], 0
	v_mov_b64_e32 v[116:117], 0
	v_mov_b64_e32 v[118:119], 0
	v_mov_b64_e32 v[120:121], 0
	v_mov_b64_e32 v[122:123], 0
	v_mov_b64_e32 v[124:125], 0
	v_mov_b64_e32 v[126:127], 0
	v_mov_b32_e32 v229, 0xbb00200b
	v_mov_b32_e32 v190, 0xbb80402b
	s_addc_u32 s83, s83, 0
	s_mov_b32 s84, -2
	s_waitcnt lgkmcnt(0)
	v_add_u32_e32 v164, 0x10000, v167
.LBB0_288:
	s_add_u32 s24, s20, 0xfff80080
	s_addc_u32 s25, s21, -1
	s_cmp_eq_u32 s84, 28
	s_cselect_b32 s77, s47, s25
	s_cselect_b32 s76, s66, s24
	s_cselect_b32 s55, s49, s83
	s_cselect_b32 s54, s69, s82
	ds_read_b128 v[128:131], v164
	ds_read_b128 v[132:135], v164 offset:1024
	ds_read_b128 v[148:151], v164 offset:2048
	ds_read_b128 v[152:155], v164 offset:3072
	ds_read_b128 v[156:159], v164 offset:16384
	ds_read_b128 v[160:163], v164 offset:17408
	ds_read_b128 v[170:173], v164 offset:18432
	ds_read_b128 v[174:177], v164 offset:19456
	s_add_i32 m0, s23, 0xc000
	ds_read_b128 v[178:181], v169
	ds_read_b128 v[186:189], v169 offset:1024
	ds_read_b128 v[192:195], v169 offset:2048
	ds_read_b128 v[202:205], v169 offset:3072
	ds_read_b128 v[206:209], v169 offset:4096
	ds_read_b128 v[210:213], v169 offset:5120
	ds_read_b128 v[214:217], v169 offset:6144
	ds_read_b128 v[218:221], v169 offset:7168
	global_load_lds_dwordx4 v144, s[20:21]
	s_add_i32 m0, s23, 0xe000
	s_nop 0
	global_load_lds_dwordx4 v146, s[20:21]
	s_waitcnt vmcnt(8)
	s_waitcnt lgkmcnt(0)
	s_barrier
	s_setprio 1
	s_waitcnt lgkmcnt(0)
	v_mfma_f32_16x16x32_bf16 v[124:127], v[128:131], v[178:181], v[124:127]
	v_mfma_f32_16x16x32_bf16 v[120:123], v[148:151], v[178:181], v[120:123]
	v_mfma_f32_16x16x32_bf16 v[108:111], v[128:131], v[192:195], v[108:111]
	v_mfma_f32_16x16x32_bf16 v[104:107], v[148:151], v[192:195], v[104:107]
	v_mfma_f32_16x16x32_bf16 v[92:95], v[128:131], v[206:209], v[92:95]
	v_mfma_f32_16x16x32_bf16 v[88:91], v[148:151], v[206:209], v[88:91]
	v_mfma_f32_16x16x32_bf16 v[76:79], v[128:131], v[214:217], v[76:79]
	v_mfma_f32_16x16x32_bf16 v[72:75], v[148:151], v[214:217], v[72:75]
	v_mfma_f32_16x16x32_bf16 v[124:127], v[132:135], v[186:189], v[124:127]
	v_mfma_f32_16x16x32_bf16 v[120:123], v[152:155], v[186:189], v[120:123]
	v_mfma_f32_16x16x32_bf16 v[108:111], v[132:135], v[202:205], v[108:111]
	v_mfma_f32_16x16x32_bf16 v[104:107], v[152:155], v[202:205], v[104:107]
	v_mfma_f32_16x16x32_bf16 v[92:95], v[132:135], v[210:213], v[92:95]
	v_mfma_f32_16x16x32_bf16 v[88:91], v[152:155], v[210:213], v[88:91]
	v_mfma_f32_16x16x32_bf16 v[76:79], v[132:135], v[218:221], v[76:79]
	v_mfma_f32_16x16x32_bf16 v[72:75], v[152:155], v[218:221], v[72:75]
	v_mfma_f32_16x16x32_bf16 v[116:119], v[156:159], v[178:181], v[116:119]
	v_mfma_f32_16x16x32_bf16 v[112:115], v[170:173], v[178:181], v[112:115]
	v_mfma_f32_16x16x32_bf16 v[100:103], v[156:159], v[192:195], v[100:103]
	v_mfma_f32_16x16x32_bf16 v[96:99], v[170:173], v[192:195], v[96:99]
	v_mfma_f32_16x16x32_bf16 v[84:87], v[156:159], v[206:209], v[84:87]
	v_mfma_f32_16x16x32_bf16 v[80:83], v[170:173], v[206:209], v[80:83]
	v_mfma_f32_16x16x32_bf16 v[68:71], v[156:159], v[214:217], v[68:71]
	v_mfma_f32_16x16x32_bf16 v[64:67], v[170:173], v[214:217], v[64:67]
	v_mfma_f32_16x16x32_bf16 v[116:119], v[160:163], v[186:189], v[116:119]
	v_mfma_f32_16x16x32_bf16 v[112:115], v[174:177], v[186:189], v[112:115]
	v_mfma_f32_16x16x32_bf16 v[100:103], v[160:163], v[202:205], v[100:103]
	v_mfma_f32_16x16x32_bf16 v[96:99], v[174:177], v[202:205], v[96:99]
	v_mfma_f32_16x16x32_bf16 v[84:87], v[160:163], v[210:213], v[84:87]
	v_mfma_f32_16x16x32_bf16 v[80:83], v[174:177], v[210:213], v[80:83]
	v_mfma_f32_16x16x32_bf16 v[68:71], v[160:163], v[218:221], v[68:71]
	v_mfma_f32_16x16x32_bf16 v[64:67], v[174:177], v[218:221], v[64:67]
	s_setprio 0
	s_barrier
; #define PG8_STAGE(bufoff, gbase, voff) do { _Pragma("unroll") for (int _i = 0; _i < 2; ++_i) \
;         __builtin_amdgcn_global_load_lds((const unsigned*)((const char*)(gbase) + (voff)[_i]), (LAS unsigned*)(lds + (bufoff) + ldsw + _i * 8192), 16, 0, 0); } while (0)
; #define PG8_LDA(dst, b, h) do { _Pragma("unroll") for (int m = 0; m < 4; ++m) _Pragma("unroll") for (int k = 0; k < 2; ++k) dst[m][k] = *(const LAS bf16x8*)(lds + PG8_SA(b, h) + aoff + m * 2048 + k * 1024); } while (0)
; #define PG8_LDB(dst, b, h) do { _Pragma("unroll") for (int n = 0; n < 2; ++n) _Pragma("unroll") for (int k = 0; k < 2; ++k) dst[n][k] = *(const LAS bf16x8*)(lds + PG8_SB(b, h) + boff + n * 2048 + k * 1024); } while (0)
; #define PG8_MMA(ai, bj, At, Bt) do { __builtin_amdgcn_s_setprio(1); _Pragma("unroll") for (int m = 0; m < 4; ++m) _Pragma("unroll") for (int n = 0; n < 2; ++n) _Pragma("unroll") for (int k = 0; k < 2; ++k) \
;         acc[ai][bj][m][n] = __builtin_amdgcn_mfma_f32_16x16x32_bf16(Bt[n][k], At[m][k], acc[ai][bj][m][n], 0, 0, 0); __builtin_amdgcn_s_setprio(0); } while (0)
; #define PG8_WAIT_V(n) asm volatile("s_waitcnt vmcnt(" #n ")" ::: "memory")
; #define PG8_WAIT_L(n) asm volatile("s_waitcnt lgkmcnt(" #n ")" ::: "memory")
; #define PG8_BAR __builtin_amdgcn_s_barrier()
; #define PG8_SCHED __builtin_amdgcn_sched_barrier(0)
; template <class Epi>
; __device__ __forceinline__ void gemm_phase(LAS unsigned char* lds, const Gemm g, const Epi& E) {
;     ...
;             PG8_WAIT_V(8); PG8_WAIT_L(0); PG8_BAR; PG8_MMA(0, 0, At, B0); PG8_MMA(0, 1, At, B1); PG8_BAR; PG8_SCHED;
;             PG8_LDA(At, 0, 1); PG8_STAGE(PG8_SB(0, 0), b2, voffB); PG8_STAGE(PG8_SB(0, 1), b2 + hstepB, voffB); PG8_STAGE(PG8_SA(0, 0), a2, voffA);
;             PG8_WAIT_V(8); PG8_WAIT_L(0); PG8_BAR; PG8_MMA(1, 0, At, B0); PG8_MMA(1, 1, At, B1); PG8_BAR; PG8_SCHED;
;             PG8_LDB(B0, 1, 0); PG8_LDB(B1, 1, 1); PG8_SCHED; PG8_LDA(At, 1, 0); PG8_STAGE(PG8_SA(0, 1), a2 + hstepA, voffA);
;             PG8_WAIT_V(8); PG8_WAIT_L(0); PG8_BAR; PG8_MMA(0, 0, At, B0); PG8_MMA(0, 1, At, B1); PG8_BAR; PG8_SCHED;
	s_add_i32 s85, s27, 0x10000
	s_mov_b32 m0, s85
	ds_read_b128 v[178:181], v169 offset:16384
	ds_read_b128 v[186:189], v169 offset:17408
	ds_read_b128 v[192:195], v169 offset:18432
	ds_read_b128 v[202:205], v169 offset:19456
	ds_read_b128 v[206:209], v169 offset:20480
	ds_read_b128 v[210:213], v169 offset:21504
	ds_read_b128 v[214:217], v169 offset:22528
	ds_read_b128 v[218:221], v169 offset:23552
	global_load_lds_dwordx4 v138, s[54:55]
	s_add_i32 m0, s85, 0x2000
	s_add_u32 s24, s54, 0x80000
	s_addc_u32 s25, s55, 0
	s_add_i32 s85, s27, 0x14000
	global_load_lds_dwordx4 v142, s[54:55]
	s_mov_b32 m0, s85
	s_nop 0
	global_load_lds_dwordx4 v138, s[24:25]
	s_add_i32 m0, s85, 0x2000
	s_nop 0
	global_load_lds_dwordx4 v142, s[24:25]
	s_mov_b32 m0, s23
	s_nop 0
	global_load_lds_dwordx4 v136, s[76:77]
	s_mov_b32 m0, s86
	s_nop 0
	global_load_lds_dwordx4 v140, s[76:77]
	s_waitcnt vmcnt(8)
	s_waitcnt lgkmcnt(0)
	s_barrier
	s_setprio 1
	s_waitcnt lgkmcnt(0)
	v_mfma_f32_16x16x32_bf16 v[60:63], v[128:131], v[178:181], v[60:63]
	v_mfma_f32_16x16x32_bf16 v[56:59], v[148:151], v[178:181], v[56:59]
	v_mfma_f32_16x16x32_bf16 v[44:47], v[128:131], v[192:195], v[44:47]
	v_mfma_f32_16x16x32_bf16 v[40:43], v[148:151], v[192:195], v[40:43]
	v_mfma_f32_16x16x32_bf16 v[28:31], v[128:131], v[206:209], v[28:31]
	v_mfma_f32_16x16x32_bf16 v[24:27], v[148:151], v[206:209], v[24:27]
	v_mfma_f32_16x16x32_bf16 v[12:15], v[128:131], v[214:217], v[12:15]
	v_mfma_f32_16x16x32_bf16 v[8:11], v[148:151], v[214:217], v[8:11]
	v_mfma_f32_16x16x32_bf16 v[60:63], v[132:135], v[186:189], v[60:63]
	v_mfma_f32_16x16x32_bf16 v[56:59], v[152:155], v[186:189], v[56:59]
	v_mfma_f32_16x16x32_bf16 v[44:47], v[132:135], v[202:205], v[44:47]
	v_mfma_f32_16x16x32_bf16 v[40:43], v[152:155], v[202:205], v[40:43]
	v_mfma_f32_16x16x32_bf16 v[28:31], v[132:135], v[210:213], v[28:31]
	v_mfma_f32_16x16x32_bf16 v[24:27], v[152:155], v[210:213], v[24:27]
	v_mfma_f32_16x16x32_bf16 v[12:15], v[132:135], v[218:221], v[12:15]
	v_mfma_f32_16x16x32_bf16 v[8:11], v[152:155], v[218:221], v[8:11]
	v_mfma_f32_16x16x32_bf16 v[52:55], v[156:159], v[178:181], v[52:55]
	v_mfma_f32_16x16x32_bf16 v[48:51], v[170:173], v[178:181], v[48:51]
	v_mfma_f32_16x16x32_bf16 v[36:39], v[156:159], v[192:195], v[36:39]
	v_mfma_f32_16x16x32_bf16 v[32:35], v[170:173], v[192:195], v[32:35]
	v_mfma_f32_16x16x32_bf16 v[20:23], v[156:159], v[206:209], v[20:23]
	v_mfma_f32_16x16x32_bf16 v[16:19], v[170:173], v[206:209], v[16:19]
	v_mfma_f32_16x16x32_bf16 v[4:7], v[156:159], v[214:217], v[4:7]
	v_mfma_f32_16x16x32_bf16 v[0:3], v[170:173], v[214:217], v[0:3]
	v_mfma_f32_16x16x32_bf16 v[52:55], v[160:163], v[186:189], v[52:55]
	v_mfma_f32_16x16x32_bf16 v[48:51], v[174:177], v[186:189], v[48:51]
	v_mfma_f32_16x16x32_bf16 v[36:39], v[160:163], v[202:205], v[36:39]
	v_mfma_f32_16x16x32_bf16 v[32:35], v[174:177], v[202:205], v[32:35]
	v_mfma_f32_16x16x32_bf16 v[20:23], v[160:163], v[210:213], v[20:23]
	v_mfma_f32_16x16x32_bf16 v[16:19], v[174:177], v[210:213], v[16:19]
	v_mfma_f32_16x16x32_bf16 v[4:7], v[160:163], v[218:221], v[4:7]
	v_mfma_f32_16x16x32_bf16 v[0:3], v[174:177], v[218:221], v[0:3]
	s_setprio 0
	s_barrier
	ds_read_b128 v[128:131], v164 offset:32768
	ds_read_b128 v[132:135], v164 offset:33792
	ds_read_b128 v[148:151], v164 offset:34816
	ds_read_b128 v[152:155], v164 offset:35840
	ds_read_b128 v[156:159], v164 offset:49152
	ds_read_b128 v[160:163], v164 offset:50176
	ds_read_b128 v[170:173], v164 offset:51200
	ds_read_b128 v[174:177], v164 offset:52224
	s_add_u32 s24, s76, 0x80000
	s_addc_u32 s25, s77, 0
	s_mov_b32 m0, s87
	ds_read_b128 v[178:181], v169 offset:32768
	ds_read_b128 v[186:189], v169 offset:33792
	ds_read_b128 v[192:195], v169 offset:34816
	ds_read_b128 v[202:205], v169 offset:35840
	ds_read_b128 v[206:209], v169 offset:36864
	ds_read_b128 v[210:213], v169 offset:37888
	ds_read_b128 v[214:217], v169 offset:38912
	ds_read_b128 v[218:221], v169 offset:39936
	global_load_lds_dwordx4 v136, s[24:25]
	s_mov_b32 m0, s17
	s_nop 0
	global_load_lds_dwordx4 v140, s[24:25]
	s_waitcnt vmcnt(8)
	s_waitcnt lgkmcnt(0)
	s_barrier
; #define PG8_STAGE(bufoff, gbase, voff) do { _Pragma("unroll") for (int _i = 0; _i < 2; ++_i) \
;         __builtin_amdgcn_global_load_lds((const unsigned*)((const char*)(gbase) + (voff)[_i]), (LAS unsigned*)(lds + (bufoff) + ldsw + _i * 8192), 16, 0, 0); } while (0)
; #define PG8_LDA(dst, b, h) do { _Pragma("unroll") for (int m = 0; m < 4; ++m) _Pragma("unroll") for (int k = 0; k < 2; ++k) dst[m][k] = *(const LAS bf16x8*)(lds + PG8_SA(b, h) + aoff + m * 2048 + k * 1024); } while (0)
; #define PG8_MMA(ai, bj, At, Bt) do { __builtin_amdgcn_s_setprio(1); _Pragma("unroll") for (int m = 0; m < 4; ++m) _Pragma("unroll") for (int n = 0; n < 2; ++n) _Pragma("unroll") for (int k = 0; k < 2; ++k) \
;         acc[ai][bj][m][n] = __builtin_amdgcn_mfma_f32_16x16x32_bf16(Bt[n][k], At[m][k], acc[ai][bj][m][n], 0, 0, 0); __builtin_amdgcn_s_setprio(0); } while (0)
; #define PG8_WAIT_V(n) asm volatile("s_waitcnt vmcnt(" #n ")" ::: "memory")
; #define PG8_WAIT_L(n) asm volatile("s_waitcnt lgkmcnt(" #n ")" ::: "memory")
; #define PG8_BAR __builtin_amdgcn_s_barrier()
; #define PG8_SCHED __builtin_amdgcn_sched_barrier(0)
; template <class Epi>
; __device__ __forceinline__ void gemm_phase(LAS unsigned char* lds, const Gemm g, const Epi& E) {
;     ...
;             PG8_WAIT_V(8); PG8_WAIT_L(0); PG8_BAR; PG8_MMA(0, 0, At, B0); PG8_MMA(0, 1, At, B1); PG8_BAR; PG8_SCHED;
;             PG8_LDA(At, 1, 1); PG8_STAGE(PG8_SB(1, 0), b3, voffB); PG8_STAGE(PG8_SB(1, 1), b3 + hstepB, voffB); PG8_STAGE(PG8_SA(1, 0), a3, voffA);
;             PG8_WAIT_V(8); PG8_WAIT_L(0); PG8_BAR; PG8_MMA(1, 0, At, B0); PG8_MMA(1, 1, At, B1); PG8_BAR; PG8_SCHED;
;         }
	s_setprio 1
	s_waitcnt lgkmcnt(0)
	v_mfma_f32_16x16x32_bf16 v[124:127], v[128:131], v[178:181], v[124:127]
	v_mfma_f32_16x16x32_bf16 v[120:123], v[148:151], v[178:181], v[120:123]
	v_mfma_f32_16x16x32_bf16 v[108:111], v[128:131], v[192:195], v[108:111]
	v_mfma_f32_16x16x32_bf16 v[104:107], v[148:151], v[192:195], v[104:107]
	v_mfma_f32_16x16x32_bf16 v[92:95], v[128:131], v[206:209], v[92:95]
	v_mfma_f32_16x16x32_bf16 v[88:91], v[148:151], v[206:209], v[88:91]
	v_mfma_f32_16x16x32_bf16 v[76:79], v[128:131], v[214:217], v[76:79]
	v_mfma_f32_16x16x32_bf16 v[72:75], v[148:151], v[214:217], v[72:75]
	v_mfma_f32_16x16x32_bf16 v[124:127], v[132:135], v[186:189], v[124:127]
	v_mfma_f32_16x16x32_bf16 v[120:123], v[152:155], v[186:189], v[120:123]
	v_mfma_f32_16x16x32_bf16 v[108:111], v[132:135], v[202:205], v[108:111]
	v_mfma_f32_16x16x32_bf16 v[104:107], v[152:155], v[202:205], v[104:107]
	v_mfma_f32_16x16x32_bf16 v[92:95], v[132:135], v[210:213], v[92:95]
	v_mfma_f32_16x16x32_bf16 v[88:91], v[152:155], v[210:213], v[88:91]
	v_mfma_f32_16x16x32_bf16 v[76:79], v[132:135], v[218:221], v[76:79]
	v_mfma_f32_16x16x32_bf16 v[72:75], v[152:155], v[218:221], v[72:75]
	v_mfma_f32_16x16x32_bf16 v[116:119], v[156:159], v[178:181], v[116:119]
	v_mfma_f32_16x16x32_bf16 v[112:115], v[170:173], v[178:181], v[112:115]
	v_mfma_f32_16x16x32_bf16 v[100:103], v[156:159], v[192:195], v[100:103]
	v_mfma_f32_16x16x32_bf16 v[96:99], v[170:173], v[192:195], v[96:99]
	v_mfma_f32_16x16x32_bf16 v[84:87], v[156:159], v[206:209], v[84:87]
	v_mfma_f32_16x16x32_bf16 v[80:83], v[170:173], v[206:209], v[80:83]
	v_mfma_f32_16x16x32_bf16 v[68:71], v[156:159], v[214:217], v[68:71]
	v_mfma_f32_16x16x32_bf16 v[64:67], v[170:173], v[214:217], v[64:67]
	v_mfma_f32_16x16x32_bf16 v[116:119], v[160:163], v[186:189], v[116:119]
	v_mfma_f32_16x16x32_bf16 v[112:115], v[174:177], v[186:189], v[112:115]
	v_mfma_f32_16x16x32_bf16 v[100:103], v[160:163], v[202:205], v[100:103]
	v_mfma_f32_16x16x32_bf16 v[96:99], v[174:177], v[202:205], v[96:99]
	v_mfma_f32_16x16x32_bf16 v[84:87], v[160:163], v[210:213], v[84:87]
	v_mfma_f32_16x16x32_bf16 v[80:83], v[174:177], v[210:213], v[80:83]
	v_mfma_f32_16x16x32_bf16 v[68:71], v[160:163], v[218:221], v[68:71]
	v_mfma_f32_16x16x32_bf16 v[64:67], v[174:177], v[218:221], v[64:67]
	s_setprio 0
	s_barrier
	s_add_i32 s85, s27, 0x18000
	s_add_u32 s24, s54, 0x80
	s_addc_u32 s25, s55, 0
	s_mov_b32 m0, s85
	ds_read_b128 v[178:181], v169 offset:49152
	ds_read_b128 v[186:189], v169 offset:50176
	ds_read_b128 v[192:195], v169 offset:51200
	ds_read_b128 v[202:205], v169 offset:52224
	ds_read_b128 v[206:209], v169 offset:53248
	ds_read_b128 v[210:213], v169 offset:54272
	ds_read_b128 v[214:217], v169 offset:55296
	ds_read_b128 v[218:221], v169 offset:56320
	global_load_lds_dwordx4 v138, s[24:25]
	s_add_i32 m0, s85, 0x2000
	s_add_i32 s85, s27, 0x1c000
	global_load_lds_dwordx4 v142, s[24:25]
	s_add_u32 s24, s54, 0x80080
	s_addc_u32 s25, s55, 0
	s_mov_b32 m0, s85
	s_nop 0
	global_load_lds_dwordx4 v138, s[24:25]
	s_add_i32 m0, s85, 0x2000
	s_nop 0
	global_load_lds_dwordx4 v142, s[24:25]
	s_add_u32 s24, s76, 0x80
	s_addc_u32 s25, s77, 0
	s_mov_b32 m0, s12
	s_nop 0
	global_load_lds_dwordx4 v136, s[24:25]
	s_mov_b32 m0, s13
	s_nop 0
	global_load_lds_dwordx4 v140, s[24:25]
	s_waitcnt vmcnt(8)
	s_waitcnt lgkmcnt(0)
	s_barrier
	s_setprio 1
	s_waitcnt lgkmcnt(0)
	v_mfma_f32_16x16x32_bf16 v[60:63], v[128:131], v[178:181], v[60:63]
	v_mfma_f32_16x16x32_bf16 v[56:59], v[148:151], v[178:181], v[56:59]
	v_mfma_f32_16x16x32_bf16 v[44:47], v[128:131], v[192:195], v[44:47]
	v_mfma_f32_16x16x32_bf16 v[40:43], v[148:151], v[192:195], v[40:43]
	v_mfma_f32_16x16x32_bf16 v[28:31], v[128:131], v[206:209], v[28:31]
	v_mfma_f32_16x16x32_bf16 v[24:27], v[148:151], v[206:209], v[24:27]
	v_mfma_f32_16x16x32_bf16 v[12:15], v[128:131], v[214:217], v[12:15]
	v_mfma_f32_16x16x32_bf16 v[8:11], v[148:151], v[214:217], v[8:11]
	v_mfma_f32_16x16x32_bf16 v[60:63], v[132:135], v[186:189], v[60:63]
	v_mfma_f32_16x16x32_bf16 v[56:59], v[152:155], v[186:189], v[56:59]
	v_mfma_f32_16x16x32_bf16 v[44:47], v[132:135], v[202:205], v[44:47]
	v_mfma_f32_16x16x32_bf16 v[40:43], v[152:155], v[202:205], v[40:43]
	v_mfma_f32_16x16x32_bf16 v[28:31], v[132:135], v[210:213], v[28:31]
	v_mfma_f32_16x16x32_bf16 v[24:27], v[152:155], v[210:213], v[24:27]
	v_mfma_f32_16x16x32_bf16 v[12:15], v[132:135], v[218:221], v[12:15]
	v_mfma_f32_16x16x32_bf16 v[8:11], v[152:155], v[218:221], v[8:11]
	v_mfma_f32_16x16x32_bf16 v[52:55], v[156:159], v[178:181], v[52:55]
	v_mfma_f32_16x16x32_bf16 v[48:51], v[170:173], v[178:181], v[48:51]
	v_mfma_f32_16x16x32_bf16 v[36:39], v[156:159], v[192:195], v[36:39]
	v_mfma_f32_16x16x32_bf16 v[32:35], v[170:173], v[192:195], v[32:35]
	v_mfma_f32_16x16x32_bf16 v[20:23], v[156:159], v[206:209], v[20:23]
	v_mfma_f32_16x16x32_bf16 v[16:19], v[170:173], v[206:209], v[16:19]
	v_mfma_f32_16x16x32_bf16 v[4:7], v[156:159], v[214:217], v[4:7]
	v_mfma_f32_16x16x32_bf16 v[0:3], v[170:173], v[214:217], v[0:3]
	v_mfma_f32_16x16x32_bf16 v[52:55], v[160:163], v[186:189], v[52:55]
	v_mfma_f32_16x16x32_bf16 v[48:51], v[174:177], v[186:189], v[48:51]
	v_mfma_f32_16x16x32_bf16 v[36:39], v[160:163], v[202:205], v[36:39]
	v_mfma_f32_16x16x32_bf16 v[32:35], v[174:177], v[202:205], v[32:35]
	v_mfma_f32_16x16x32_bf16 v[20:23], v[160:163], v[210:213], v[20:23]
	v_mfma_f32_16x16x32_bf16 v[16:19], v[174:177], v[210:213], v[16:19]
	v_mfma_f32_16x16x32_bf16 v[4:7], v[160:163], v[218:221], v[4:7]
	v_mfma_f32_16x16x32_bf16 v[0:3], v[174:177], v[218:221], v[0:3]
	s_setprio 0
	s_barrier
	s_add_i32 s84, s84, 2
	s_add_u32 s20, s20, 0x100
	s_addc_u32 s21, s21, 0
	s_add_u32 s82, s82, 0x100
	s_addc_u32 s83, s83, 0
	s_cmp_gt_u32 s84, 29
	s_cbranch_scc0 .LBB0_288
	s_and_b64 vcc, exec, s[44:45]
	s_cbranch_vccz .LBB0_291
	s_barrier

; #define PG8_STAGE(bufoff, gbase, voff) do { _Pragma("unroll") for (int _i = 0; _i < 2; ++_i) \
;         __builtin_amdgcn_global_load_lds((const unsigned*)((const char*)(gbase) + (voff)[_i]), (LAS unsigned*)(lds + (bufoff) + ldsw + _i * 8192), 16, 0, 0); } while (0)
; #define PG8_LDA(dst, b, h) do { _Pragma("unroll") for (int m = 0; m < 4; ++m) _Pragma("unroll") for (int k = 0; k < 2; ++k) dst[m][k] = *(const LAS bf16x8*)(lds + PG8_SA(b, h) + aoff + m * 2048 + k * 1024); } while (0)
; #define PG8_LDB(dst, b, h) do { _Pragma("unroll") for (int n = 0; n < 2; ++n) _Pragma("unroll") for (int k = 0; k < 2; ++k) dst[n][k] = *(const LAS bf16x8*)(lds + PG8_SB(b, h) + boff + n * 2048 + k * 1024); } while (0)
; #define PG8_MMA(ai, bj, At, Bt) do { __builtin_amdgcn_s_setprio(1); _Pragma("unroll") for (int m = 0; m < 4; ++m) _Pragma("unroll") for (int n = 0; n < 2; ++n) _Pragma("unroll") for (int k = 0; k < 2; ++k) \
;         acc[ai][bj][m][n] = __builtin_amdgcn_mfma_f32_16x16x32_bf16(Bt[n][k], At[m][k], acc[ai][bj][m][n], 0, 0, 0); __builtin_amdgcn_s_setprio(0); } while (0)
; #define PG8_WAIT_V(n) asm volatile("s_waitcnt vmcnt(" #n ")" ::: "memory")
; #define PG8_WAIT_L(n) asm volatile("s_waitcnt lgkmcnt(" #n ")" ::: "memory")
; #define PG8_BAR __builtin_amdgcn_s_barrier()
; #define PG8_SCHED __builtin_amdgcn_sched_barrier(0)
; template <class Epi>
; __device__ __forceinline__ void gemm_phase(LAS unsigned char* lds, const Gemm g, const Epi& E) {
;     ...
;         for (int t = 0; t < nt; t += 2) {
;             const bool last = (t == nt - 2);
;             const char* a1 = cA + (size_t)(t + 1) * kstep;
;             const char* a2 = last ? nA : cA + (size_t)(t + 2) * kstep; const char* b2 = last ? nB : cB + (size_t)(t + 2) * kstep;
;             const char* a3 = a2 + kstep; const char* b3 = b2 + kstep;
;             PG8_LDB(B0, 0, 0); PG8_LDB(B1, 0, 1); PG8_SCHED; PG8_LDA(At, 0, 0); PG8_STAGE(PG8_SA(1, 1), a1 + hstepA, voffA);
;             PG8_WAIT_V(8); PG8_WAIT_L(0); PG8_BAR; PG8_MMA(0, 0, At, B0); PG8_MMA(0, 1, At, B1); PG8_BAR; PG8_SCHED;
;     ...
; #pragma unroll
;         for (int a = 0; a < 2; ++a)
; #pragma unroll
;             for (int b = 0; b < 2; ++b)
; #pragma unroll
;                 for (int m = 0; m < 4; ++m)
; #pragma unroll
;                     for (int n = 0; n < 2; ++n) acc[a][b][m][n] = (f32x4){0.f, 0.f, 0.f, 0.f};
;         cur = nxt; cA = nA; cB = nB; ++ui;
.LBB0_370:
	s_ashr_i32 s39, s38, 31
	s_lshl_b64 s[48:49], s[38:39], 19
	s_add_u32 s48, s8, s48
	s_addc_u32 s49, s9, s49
	s_and_b64 s[54:55], s[40:41], exec
	s_cselect_b32 s39, s49, s21
	s_cselect_b32 s43, s48, s20
	s_ashr_i32 s47, s46, 31
	s_lshl_b64 s[54:55], s[46:47], 19
	s_add_u32 s56, s6, s54
	s_addc_u32 s57, s7, s55
	s_and_b64 s[54:55], s[40:41], exec
	s_cselect_b32 s45, s57, s23
	s_cselect_b32 s47, s56, s22
	s_add_u32 s20, s20, 0x40080
	s_addc_u32 s21, s21, 0
	s_add_u32 s77, s22, 0x100
	v_mov_b64_e32 v[0:1], 0
	v_mov_b64_e32 v[2:3], 0
	v_mov_b64_e32 v[4:5], 0
	v_mov_b64_e32 v[6:7], 0
	v_mov_b64_e32 v[8:9], 0
	v_mov_b64_e32 v[10:11], 0
	v_mov_b64_e32 v[12:13], 0
	v_mov_b64_e32 v[14:15], 0
	v_mov_b64_e32 v[16:17], 0
	v_mov_b64_e32 v[18:19], 0
	v_mov_b64_e32 v[20:21], 0
	v_mov_b64_e32 v[22:23], 0
	v_mov_b64_e32 v[24:25], 0
	v_mov_b64_e32 v[26:27], 0
	v_mov_b64_e32 v[28:29], 0
	v_mov_b64_e32 v[30:31], 0
	v_mov_b64_e32 v[32:33], 0
	v_mov_b64_e32 v[34:35], 0
	v_mov_b64_e32 v[36:37], 0
	v_mov_b64_e32 v[38:39], 0
	v_mov_b64_e32 v[40:41], 0
	v_mov_b64_e32 v[42:43], 0
	v_mov_b64_e32 v[44:45], 0
	v_mov_b64_e32 v[46:47], 0
	v_mov_b64_e32 v[48:49], 0
	v_mov_b64_e32 v[50:51], 0
	v_mov_b64_e32 v[52:53], 0
	v_mov_b64_e32 v[54:55], 0
	v_mov_b64_e32 v[56:57], 0
	v_mov_b64_e32 v[58:59], 0
	v_mov_b64_e32 v[60:61], 0
	v_mov_b64_e32 v[62:63], 0
	v_mov_b64_e32 v[64:65], 0
	v_mov_b64_e32 v[66:67], 0
	v_mov_b64_e32 v[68:69], 0
	v_mov_b64_e32 v[70:71], 0
	v_mov_b64_e32 v[72:73], 0
	v_mov_b64_e32 v[74:75], 0
	v_mov_b64_e32 v[76:77], 0
	v_mov_b64_e32 v[78:79], 0
	v_mov_b64_e32 v[80:81], 0
	v_mov_b64_e32 v[82:83], 0
	v_mov_b64_e32 v[84:85], 0
	v_mov_b64_e32 v[86:87], 0
	v_mov_b64_e32 v[88:89], 0
	v_mov_b64_e32 v[90:91], 0
	v_mov_b64_e32 v[92:93], 0
	v_mov_b64_e32 v[94:95], 0
	v_mov_b64_e32 v[96:97], 0
	v_mov_b64_e32 v[98:99], 0
	v_mov_b64_e32 v[100:101], 0
	v_mov_b64_e32 v[102:103], 0
	v_mov_b64_e32 v[104:105], 0
	v_mov_b64_e32 v[106:107], 0
	v_mov_b64_e32 v[108:109], 0
	v_mov_b64_e32 v[110:111], 0
	v_mov_b64_e32 v[112:113], 0
	v_mov_b64_e32 v[114:115], 0
	v_mov_b64_e32 v[116:117], 0
	v_mov_b64_e32 v[118:119], 0
	v_mov_b64_e32 v[120:121], 0
	v_mov_b64_e32 v[122:123], 0
	v_mov_b64_e32 v[124:125], 0
	v_mov_b64_e32 v[126:127], 0
	s_addc_u32 s82, s23, 0
	s_mov_b32 s83, -2
	v_add_u32_e32 v186, 0x10000, v150
.LBB0_371:
	s_add_u32 s22, s20, 0xfffc0080
	s_addc_u32 s23, s21, -1
	s_cmp_eq_u32 s83, 12
	s_cselect_b32 s55, s39, s23
	s_cselect_b32 s54, s43, s22
	s_cselect_b32 s23, s45, s82
	s_cselect_b32 s22, s47, s77
	ds_read_b128 v[144:147], v186
	ds_read_b128 v[154:157], v186 offset:1024
	ds_read_b128 v[158:161], v186 offset:2048
	ds_read_b128 v[162:165], v186 offset:3072
	ds_read_b128 v[166:169], v186 offset:16384
	ds_read_b128 v[170:173], v186 offset:17408
	ds_read_b128 v[174:177], v186 offset:18432
	ds_read_b128 v[178:181], v186 offset:19456
	s_add_i32 m0, s18, 0xc000
	ds_read_b128 v[202:205], v153
	ds_read_b128 v[206:209], v153 offset:1024
	ds_read_b128 v[210:213], v153 offset:2048
	ds_read_b128 v[214:217], v153 offset:3072
	ds_read_b128 v[218:221], v153 offset:4096
	ds_read_b128 v[222:225], v153 offset:5120
	ds_read_b128 v[244:247], v153 offset:6144
	ds_read_b128 v[248:251], v153 offset:7168
	global_load_lds_dwordx4 v140, s[20:21]
	s_add_i32 m0, s18, 0xe000
	s_nop 0
	global_load_lds_dwordx4 v142, s[20:21]
	s_waitcnt vmcnt(8)
	s_waitcnt lgkmcnt(0)
	s_barrier
	s_setprio 1
	s_waitcnt lgkmcnt(0)
	v_mfma_f32_16x16x32_bf16 v[124:127], v[144:147], v[202:205], v[124:127]
	v_mfma_f32_16x16x32_bf16 v[120:123], v[158:161], v[202:205], v[120:123]
	v_mfma_f32_16x16x32_bf16 v[108:111], v[144:147], v[210:213], v[108:111]
	v_mfma_f32_16x16x32_bf16 v[104:107], v[158:161], v[210:213], v[104:107]
	v_mfma_f32_16x16x32_bf16 v[92:95], v[144:147], v[218:221], v[92:95]
	v_mfma_f32_16x16x32_bf16 v[88:91], v[158:161], v[218:221], v[88:91]
	v_mfma_f32_16x16x32_bf16 v[76:79], v[144:147], v[244:247], v[76:79]
	v_mfma_f32_16x16x32_bf16 v[72:75], v[158:161], v[244:247], v[72:75]
	v_mfma_f32_16x16x32_bf16 v[124:127], v[154:157], v[206:209], v[124:127]
	v_mfma_f32_16x16x32_bf16 v[120:123], v[162:165], v[206:209], v[120:123]
	v_mfma_f32_16x16x32_bf16 v[108:111], v[154:157], v[214:217], v[108:111]
	v_mfma_f32_16x16x32_bf16 v[104:107], v[162:165], v[214:217], v[104:107]
	v_mfma_f32_16x16x32_bf16 v[92:95], v[154:157], v[222:225], v[92:95]
	v_mfma_f32_16x16x32_bf16 v[88:91], v[162:165], v[222:225], v[88:91]
	v_mfma_f32_16x16x32_bf16 v[76:79], v[154:157], v[248:251], v[76:79]
	v_mfma_f32_16x16x32_bf16 v[72:75], v[162:165], v[248:251], v[72:75]
	v_mfma_f32_16x16x32_bf16 v[116:119], v[166:169], v[202:205], v[116:119]
	v_mfma_f32_16x16x32_bf16 v[112:115], v[174:177], v[202:205], v[112:115]
	v_mfma_f32_16x16x32_bf16 v[100:103], v[166:169], v[210:213], v[100:103]
	v_mfma_f32_16x16x32_bf16 v[96:99], v[174:177], v[210:213], v[96:99]
	v_mfma_f32_16x16x32_bf16 v[84:87], v[166:169], v[218:221], v[84:87]
	v_mfma_f32_16x16x32_bf16 v[80:83], v[174:177], v[218:221], v[80:83]
	v_mfma_f32_16x16x32_bf16 v[68:71], v[166:169], v[244:247], v[68:71]
	v_mfma_f32_16x16x32_bf16 v[64:67], v[174:177], v[244:247], v[64:67]
	v_mfma_f32_16x16x32_bf16 v[116:119], v[170:173], v[206:209], v[116:119]
	v_mfma_f32_16x16x32_bf16 v[112:115], v[178:181], v[206:209], v[112:115]
	v_mfma_f32_16x16x32_bf16 v[100:103], v[170:173], v[214:217], v[100:103]
	v_mfma_f32_16x16x32_bf16 v[96:99], v[178:181], v[214:217], v[96:99]
	v_mfma_f32_16x16x32_bf16 v[84:87], v[170:173], v[222:225], v[84:87]
	v_mfma_f32_16x16x32_bf16 v[80:83], v[178:181], v[222:225], v[80:83]
	v_mfma_f32_16x16x32_bf16 v[68:71], v[170:173], v[248:251], v[68:71]
	v_mfma_f32_16x16x32_bf16 v[64:67], v[178:181], v[248:251], v[64:67]
	s_setprio 0
	s_barrier
; #define PG8_STAGE(bufoff, gbase, voff) do { _Pragma("unroll") for (int _i = 0; _i < 2; ++_i) \
;         __builtin_amdgcn_global_load_lds((const unsigned*)((const char*)(gbase) + (voff)[_i]), (LAS unsigned*)(lds + (bufoff) + ldsw + _i * 8192), 16, 0, 0); } while (0)
; #define PG8_LDA(dst, b, h) do { _Pragma("unroll") for (int m = 0; m < 4; ++m) _Pragma("unroll") for (int k = 0; k < 2; ++k) dst[m][k] = *(const LAS bf16x8*)(lds + PG8_SA(b, h) + aoff + m * 2048 + k * 1024); } while (0)
; #define PG8_LDB(dst, b, h) do { _Pragma("unroll") for (int n = 0; n < 2; ++n) _Pragma("unroll") for (int k = 0; k < 2; ++k) dst[n][k] = *(const LAS bf16x8*)(lds + PG8_SB(b, h) + boff + n * 2048 + k * 1024); } while (0)
; #define PG8_MMA(ai, bj, At, Bt) do { __builtin_amdgcn_s_setprio(1); _Pragma("unroll") for (int m = 0; m < 4; ++m) _Pragma("unroll") for (int n = 0; n < 2; ++n) _Pragma("unroll") for (int k = 0; k < 2; ++k) \
;         acc[ai][bj][m][n] = __builtin_amdgcn_mfma_f32_16x16x32_bf16(Bt[n][k], At[m][k], acc[ai][bj][m][n], 0, 0, 0); __builtin_amdgcn_s_setprio(0); } while (0)
; #define PG8_WAIT_V(n) asm volatile("s_waitcnt vmcnt(" #n ")" ::: "memory")
; #define PG8_WAIT_L(n) asm volatile("s_waitcnt lgkmcnt(" #n ")" ::: "memory")
; #define PG8_BAR __builtin_amdgcn_s_barrier()
; #define PG8_SCHED __builtin_amdgcn_sched_barrier(0)
; template <class Epi>
; __device__ __forceinline__ void gemm_phase(LAS unsigned char* lds, const Gemm g, const Epi& E) {
;     ...
;             PG8_WAIT_V(8); PG8_WAIT_L(0); PG8_BAR; PG8_MMA(0, 0, At, B0); PG8_MMA(0, 1, At, B1); PG8_BAR; PG8_SCHED;
;             PG8_LDA(At, 0, 1); PG8_STAGE(PG8_SB(0, 0), b2, voffB); PG8_STAGE(PG8_SB(0, 1), b2 + hstepB, voffB); PG8_STAGE(PG8_SA(0, 0), a2, voffA);
;             PG8_WAIT_V(8); PG8_WAIT_L(0); PG8_BAR; PG8_MMA(1, 0, At, B0); PG8_MMA(1, 1, At, B1); PG8_BAR; PG8_SCHED;
;             PG8_LDB(B0, 1, 0); PG8_LDB(B1, 1, 1); PG8_SCHED; PG8_LDA(At, 1, 0); PG8_STAGE(PG8_SA(0, 1), a2 + hstepA, voffA);
;             PG8_WAIT_V(8); PG8_WAIT_L(0); PG8_BAR; PG8_MMA(0, 0, At, B0); PG8_MMA(0, 1, At, B1); PG8_BAR; PG8_SCHED;
	s_add_i32 s24, s17, 0x10000
	s_mov_b32 m0, s24
	ds_read_b128 v[202:205], v153 offset:16384
	ds_read_b128 v[206:209], v153 offset:17408
	ds_read_b128 v[210:213], v153 offset:18432
	ds_read_b128 v[214:217], v153 offset:19456
	ds_read_b128 v[218:221], v153 offset:20480
	ds_read_b128 v[222:225], v153 offset:21504
	ds_read_b128 v[244:247], v153 offset:22528
	ds_read_b128 v[248:251], v153 offset:23552
	global_load_lds_dwordx4 v130, s[22:23]
	s_add_i32 m0, s24, 0x2000
	s_add_u32 s84, s22, 0x40000
	s_addc_u32 s85, s23, 0
	s_add_i32 s24, s17, 0x14000
	global_load_lds_dwordx4 v134, s[22:23]
	s_mov_b32 m0, s24
	s_nop 0
	global_load_lds_dwordx4 v130, s[84:85]
	s_add_i32 m0, s24, 0x2000
	s_nop 0
	global_load_lds_dwordx4 v134, s[84:85]
	s_mov_b32 m0, s18
	s_nop 0
	global_load_lds_dwordx4 v128, s[54:55]
	s_mov_b32 m0, s19
	s_nop 0
	global_load_lds_dwordx4 v132, s[54:55]
	s_waitcnt vmcnt(8)
	s_waitcnt lgkmcnt(0)
	s_barrier
	s_setprio 1
	s_waitcnt lgkmcnt(0)
	v_mfma_f32_16x16x32_bf16 v[60:63], v[144:147], v[202:205], v[60:63]
	v_mfma_f32_16x16x32_bf16 v[56:59], v[158:161], v[202:205], v[56:59]
	v_mfma_f32_16x16x32_bf16 v[44:47], v[144:147], v[210:213], v[44:47]
	v_mfma_f32_16x16x32_bf16 v[40:43], v[158:161], v[210:213], v[40:43]
	v_mfma_f32_16x16x32_bf16 v[28:31], v[144:147], v[218:221], v[28:31]
	v_mfma_f32_16x16x32_bf16 v[24:27], v[158:161], v[218:221], v[24:27]
	v_mfma_f32_16x16x32_bf16 v[12:15], v[144:147], v[244:247], v[12:15]
	v_mfma_f32_16x16x32_bf16 v[8:11], v[158:161], v[244:247], v[8:11]
	v_mfma_f32_16x16x32_bf16 v[60:63], v[154:157], v[206:209], v[60:63]
	v_mfma_f32_16x16x32_bf16 v[56:59], v[162:165], v[206:209], v[56:59]
	v_mfma_f32_16x16x32_bf16 v[44:47], v[154:157], v[214:217], v[44:47]
	v_mfma_f32_16x16x32_bf16 v[40:43], v[162:165], v[214:217], v[40:43]
	v_mfma_f32_16x16x32_bf16 v[28:31], v[154:157], v[222:225], v[28:31]
	v_mfma_f32_16x16x32_bf16 v[24:27], v[162:165], v[222:225], v[24:27]
	v_mfma_f32_16x16x32_bf16 v[12:15], v[154:157], v[248:251], v[12:15]
	v_mfma_f32_16x16x32_bf16 v[8:11], v[162:165], v[248:251], v[8:11]
	v_mfma_f32_16x16x32_bf16 v[52:55], v[166:169], v[202:205], v[52:55]
	v_mfma_f32_16x16x32_bf16 v[48:51], v[174:177], v[202:205], v[48:51]
	v_mfma_f32_16x16x32_bf16 v[36:39], v[166:169], v[210:213], v[36:39]
	v_mfma_f32_16x16x32_bf16 v[32:35], v[174:177], v[210:213], v[32:35]
	v_mfma_f32_16x16x32_bf16 v[20:23], v[166:169], v[218:221], v[20:23]
	v_mfma_f32_16x16x32_bf16 v[16:19], v[174:177], v[218:221], v[16:19]
	v_mfma_f32_16x16x32_bf16 v[4:7], v[166:169], v[244:247], v[4:7]
	v_mfma_f32_16x16x32_bf16 v[0:3], v[174:177], v[244:247], v[0:3]
	v_mfma_f32_16x16x32_bf16 v[52:55], v[170:173], v[206:209], v[52:55]
	v_mfma_f32_16x16x32_bf16 v[48:51], v[178:181], v[206:209], v[48:51]
	v_mfma_f32_16x16x32_bf16 v[36:39], v[170:173], v[214:217], v[36:39]
	v_mfma_f32_16x16x32_bf16 v[32:35], v[178:181], v[214:217], v[32:35]
	v_mfma_f32_16x16x32_bf16 v[20:23], v[170:173], v[222:225], v[20:23]
	v_mfma_f32_16x16x32_bf16 v[16:19], v[178:181], v[222:225], v[16:19]
	v_mfma_f32_16x16x32_bf16 v[4:7], v[170:173], v[248:251], v[4:7]
	v_mfma_f32_16x16x32_bf16 v[0:3], v[178:181], v[248:251], v[0:3]
	s_setprio 0
	s_barrier
	ds_read_b128 v[144:147], v186 offset:32768
	ds_read_b128 v[154:157], v186 offset:33792
	ds_read_b128 v[158:161], v186 offset:34816
	ds_read_b128 v[162:165], v186 offset:35840
	ds_read_b128 v[166:169], v186 offset:49152
	ds_read_b128 v[170:173], v186 offset:50176
	ds_read_b128 v[174:177], v186 offset:51200
	ds_read_b128 v[178:181], v186 offset:52224
	s_add_u32 s84, s54, 0x40000
	s_addc_u32 s85, s55, 0
	s_mov_b32 m0, s26
	ds_read_b128 v[202:205], v153 offset:32768
	ds_read_b128 v[206:209], v153 offset:33792
	ds_read_b128 v[210:213], v153 offset:34816
	ds_read_b128 v[214:217], v153 offset:35840
	ds_read_b128 v[218:221], v153 offset:36864
	ds_read_b128 v[222:225], v153 offset:37888
	ds_read_b128 v[244:247], v153 offset:38912
	ds_read_b128 v[248:251], v153 offset:39936
	global_load_lds_dwordx4 v128, s[84:85]
	s_mov_b32 m0, s27
	s_nop 0
	global_load_lds_dwordx4 v132, s[84:85]
	s_waitcnt vmcnt(8)
	s_waitcnt lgkmcnt(0)
	s_barrier
; #define PG8_STAGE(bufoff, gbase, voff) do { _Pragma("unroll") for (int _i = 0; _i < 2; ++_i) \
;         __builtin_amdgcn_global_load_lds((const unsigned*)((const char*)(gbase) + (voff)[_i]), (LAS unsigned*)(lds + (bufoff) + ldsw + _i * 8192), 16, 0, 0); } while (0)
; #define PG8_LDA(dst, b, h) do { _Pragma("unroll") for (int m = 0; m < 4; ++m) _Pragma("unroll") for (int k = 0; k < 2; ++k) dst[m][k] = *(const LAS bf16x8*)(lds + PG8_SA(b, h) + aoff + m * 2048 + k * 1024); } while (0)
; #define PG8_MMA(ai, bj, At, Bt) do { __builtin_amdgcn_s_setprio(1); _Pragma("unroll") for (int m = 0; m < 4; ++m) _Pragma("unroll") for (int n = 0; n < 2; ++n) _Pragma("unroll") for (int k = 0; k < 2; ++k) \
;         acc[ai][bj][m][n] = __builtin_amdgcn_mfma_f32_16x16x32_bf16(Bt[n][k], At[m][k], acc[ai][bj][m][n], 0, 0, 0); __builtin_amdgcn_s_setprio(0); } while (0)
; #define PG8_WAIT_V(n) asm volatile("s_waitcnt vmcnt(" #n ")" ::: "memory")
; #define PG8_WAIT_L(n) asm volatile("s_waitcnt lgkmcnt(" #n ")" ::: "memory")
; #define PG8_BAR __builtin_amdgcn_s_barrier()
; #define PG8_SCHED __builtin_amdgcn_sched_barrier(0)
; template <class Epi>
; __device__ __forceinline__ void gemm_phase(LAS unsigned char* lds, const Gemm g, const Epi& E) {
;     ...
;             PG8_WAIT_V(8); PG8_WAIT_L(0); PG8_BAR; PG8_MMA(0, 0, At, B0); PG8_MMA(0, 1, At, B1); PG8_BAR; PG8_SCHED;
;             PG8_LDA(At, 1, 1); PG8_STAGE(PG8_SB(1, 0), b3, voffB); PG8_STAGE(PG8_SB(1, 1), b3 + hstepB, voffB); PG8_STAGE(PG8_SA(1, 0), a3, voffA);
;             PG8_WAIT_V(8); PG8_WAIT_L(0); PG8_BAR; PG8_MMA(1, 0, At, B0); PG8_MMA(1, 1, At, B1); PG8_BAR; PG8_SCHED;
;         }
	s_setprio 1
	s_waitcnt lgkmcnt(0)
	v_mfma_f32_16x16x32_bf16 v[124:127], v[144:147], v[202:205], v[124:127]
	v_mfma_f32_16x16x32_bf16 v[120:123], v[158:161], v[202:205], v[120:123]
	v_mfma_f32_16x16x32_bf16 v[108:111], v[144:147], v[210:213], v[108:111]
	v_mfma_f32_16x16x32_bf16 v[104:107], v[158:161], v[210:213], v[104:107]
	v_mfma_f32_16x16x32_bf16 v[92:95], v[144:147], v[218:221], v[92:95]
	v_mfma_f32_16x16x32_bf16 v[88:91], v[158:161], v[218:221], v[88:91]
	v_mfma_f32_16x16x32_bf16 v[76:79], v[144:147], v[244:247], v[76:79]
	v_mfma_f32_16x16x32_bf16 v[72:75], v[158:161], v[244:247], v[72:75]
	v_mfma_f32_16x16x32_bf16 v[124:127], v[154:157], v[206:209], v[124:127]
	v_mfma_f32_16x16x32_bf16 v[120:123], v[162:165], v[206:209], v[120:123]
	v_mfma_f32_16x16x32_bf16 v[108:111], v[154:157], v[214:217], v[108:111]
	v_mfma_f32_16x16x32_bf16 v[104:107], v[162:165], v[214:217], v[104:107]
	v_mfma_f32_16x16x32_bf16 v[92:95], v[154:157], v[222:225], v[92:95]
	v_mfma_f32_16x16x32_bf16 v[88:91], v[162:165], v[222:225], v[88:91]
	v_mfma_f32_16x16x32_bf16 v[76:79], v[154:157], v[248:251], v[76:79]
	v_mfma_f32_16x16x32_bf16 v[72:75], v[162:165], v[248:251], v[72:75]
	v_mfma_f32_16x16x32_bf16 v[116:119], v[166:169], v[202:205], v[116:119]
	v_mfma_f32_16x16x32_bf16 v[112:115], v[174:177], v[202:205], v[112:115]
	v_mfma_f32_16x16x32_bf16 v[100:103], v[166:169], v[210:213], v[100:103]
	v_mfma_f32_16x16x32_bf16 v[96:99], v[174:177], v[210:213], v[96:99]
	v_mfma_f32_16x16x32_bf16 v[84:87], v[166:169], v[218:221], v[84:87]
	v_mfma_f32_16x16x32_bf16 v[80:83], v[174:177], v[218:221], v[80:83]
	v_mfma_f32_16x16x32_bf16 v[68:71], v[166:169], v[244:247], v[68:71]
	v_mfma_f32_16x16x32_bf16 v[64:67], v[174:177], v[244:247], v[64:67]
	v_mfma_f32_16x16x32_bf16 v[116:119], v[170:173], v[206:209], v[116:119]
	v_mfma_f32_16x16x32_bf16 v[112:115], v[178:181], v[206:209], v[112:115]
	v_mfma_f32_16x16x32_bf16 v[100:103], v[170:173], v[214:217], v[100:103]
	v_mfma_f32_16x16x32_bf16 v[96:99], v[178:181], v[214:217], v[96:99]
	v_mfma_f32_16x16x32_bf16 v[84:87], v[170:173], v[222:225], v[84:87]
	v_mfma_f32_16x16x32_bf16 v[80:83], v[178:181], v[222:225], v[80:83]
	v_mfma_f32_16x16x32_bf16 v[68:71], v[170:173], v[248:251], v[68:71]
	v_mfma_f32_16x16x32_bf16 v[64:67], v[178:181], v[248:251], v[64:67]
	s_setprio 0
	s_barrier
	s_add_i32 s24, s17, 0x18000
	s_add_u32 s84, s22, 0x80
	s_addc_u32 s85, s23, 0
	s_mov_b32 m0, s24
	ds_read_b128 v[202:205], v153 offset:49152
	ds_read_b128 v[206:209], v153 offset:50176
	ds_read_b128 v[210:213], v153 offset:51200
	ds_read_b128 v[214:217], v153 offset:52224
	ds_read_b128 v[218:221], v153 offset:53248
	ds_read_b128 v[222:225], v153 offset:54272
	ds_read_b128 v[244:247], v153 offset:55296
	ds_read_b128 v[248:251], v153 offset:56320
	global_load_lds_dwordx4 v130, s[84:85]
	s_add_i32 m0, s24, 0x2000
	s_add_u32 s22, s22, 0x40080
	s_addc_u32 s23, s23, 0
	s_add_i32 s24, s17, 0x1c000
	global_load_lds_dwordx4 v134, s[84:85]
	s_mov_b32 m0, s24
	s_nop 0
	global_load_lds_dwordx4 v130, s[22:23]
	s_add_i32 m0, s24, 0x2000
	s_nop 0
	global_load_lds_dwordx4 v134, s[22:23]
	s_add_u32 s84, s54, 0x80
	s_addc_u32 s85, s55, 0
	s_mov_b32 m0, s68
	s_nop 0
	global_load_lds_dwordx4 v128, s[84:85]
	s_mov_b32 m0, s69
	s_nop 0
	global_load_lds_dwordx4 v132, s[84:85]
	s_waitcnt vmcnt(8)
	s_waitcnt lgkmcnt(0)
	s_barrier
	s_setprio 1
	s_waitcnt lgkmcnt(0)
	v_mfma_f32_16x16x32_bf16 v[60:63], v[144:147], v[202:205], v[60:63]
	v_mfma_f32_16x16x32_bf16 v[56:59], v[158:161], v[202:205], v[56:59]
	v_mfma_f32_16x16x32_bf16 v[44:47], v[144:147], v[210:213], v[44:47]
	v_mfma_f32_16x16x32_bf16 v[40:43], v[158:161], v[210:213], v[40:43]
	v_mfma_f32_16x16x32_bf16 v[28:31], v[144:147], v[218:221], v[28:31]
	v_mfma_f32_16x16x32_bf16 v[24:27], v[158:161], v[218:221], v[24:27]
	v_mfma_f32_16x16x32_bf16 v[12:15], v[144:147], v[244:247], v[12:15]
	v_mfma_f32_16x16x32_bf16 v[8:11], v[158:161], v[244:247], v[8:11]
	v_mfma_f32_16x16x32_bf16 v[60:63], v[154:157], v[206:209], v[60:63]
	v_mfma_f32_16x16x32_bf16 v[56:59], v[162:165], v[206:209], v[56:59]
	v_mfma_f32_16x16x32_bf16 v[44:47], v[154:157], v[214:217], v[44:47]
	v_mfma_f32_16x16x32_bf16 v[40:43], v[162:165], v[214:217], v[40:43]
	v_mfma_f32_16x16x32_bf16 v[28:31], v[154:157], v[222:225], v[28:31]
	v_mfma_f32_16x16x32_bf16 v[24:27], v[162:165], v[222:225], v[24:27]
	v_mfma_f32_16x16x32_bf16 v[12:15], v[154:157], v[248:251], v[12:15]
	v_mfma_f32_16x16x32_bf16 v[8:11], v[162:165], v[248:251], v[8:11]
	v_mfma_f32_16x16x32_bf16 v[52:55], v[166:169], v[202:205], v[52:55]
	v_mfma_f32_16x16x32_bf16 v[48:51], v[174:177], v[202:205], v[48:51]
	v_mfma_f32_16x16x32_bf16 v[36:39], v[166:169], v[210:213], v[36:39]
	v_mfma_f32_16x16x32_bf16 v[32:35], v[174:177], v[210:213], v[32:35]
	v_mfma_f32_16x16x32_bf16 v[20:23], v[166:169], v[218:221], v[20:23]
	v_mfma_f32_16x16x32_bf16 v[16:19], v[174:177], v[218:221], v[16:19]
	v_mfma_f32_16x16x32_bf16 v[4:7], v[166:169], v[244:247], v[4:7]
	v_mfma_f32_16x16x32_bf16 v[0:3], v[174:177], v[244:247], v[0:3]
	v_mfma_f32_16x16x32_bf16 v[52:55], v[170:173], v[206:209], v[52:55]
	v_mfma_f32_16x16x32_bf16 v[48:51], v[178:181], v[206:209], v[48:51]
	v_mfma_f32_16x16x32_bf16 v[36:39], v[170:173], v[214:217], v[36:39]
	v_mfma_f32_16x16x32_bf16 v[32:35], v[178:181], v[214:217], v[32:35]
	v_mfma_f32_16x16x32_bf16 v[20:23], v[170:173], v[222:225], v[20:23]
	v_mfma_f32_16x16x32_bf16 v[16:19], v[178:181], v[222:225], v[16:19]
	v_mfma_f32_16x16x32_bf16 v[4:7], v[170:173], v[248:251], v[4:7]
	v_mfma_f32_16x16x32_bf16 v[0:3], v[178:181], v[248:251], v[0:3]
	s_setprio 0
	s_barrier
	s_add_i32 s83, s83, 2
	s_add_u32 s20, s20, 0x100
	s_addc_u32 s21, s21, 0
	s_add_u32 s77, s77, 0x100
	s_addc_u32 s82, s82, 0
	s_cmp_gt_u32 s83, 13
	s_cbranch_scc0 .LBB0_371
	s_and_b64 vcc, exec, s[36:37]
	s_cbranch_vccz .LBB0_374
	s_barrier
